# combo14 = combo10 with the mlB U-row prefetch three batches ahead instead of two
# baseline (speedup 1.0000x reference)
.LBB0_1447:
	s_or_b64 exec, exec, s[4:5]
	s_waitcnt vmcnt(0) lgkmcnt(0)
	s_mov_b32 s100, 0x3b780000
	s_mov_b32 s101, 0
	v_lshl_add_u64 v[62:63], s[6:7], 0, v[6:7]
	v_lshl_add_u64 v[62:63], v[62:63], 0, s[100:101]
	global_load_dword v60, v[62:63], off
	s_mov_b32 s100, 0x10000
	v_lshl_add_u64 v[62:63], v[62:63], 0, s[100:101]
	global_load_dword v60, v[62:63], off
	v_lshl_add_u64 v[62:63], v[62:63], 0, s[100:101]
	global_load_dword v60, v[62:63], off
	v_lshl_add_u64 v[62:63], v[62:63], 0, s[100:101]
	global_load_dword v60, v[62:63], off
	v_lshl_add_u64 v[62:63], v[62:63], 0, s[100:101]
	global_load_dword v60, v[62:63], off
	v_lshl_add_u64 v[62:63], v[62:63], 0, s[100:101]
	global_load_dword v60, v[62:63], off
	v_lshl_add_u64 v[62:63], v[62:63], 0, s[100:101]
	global_load_dword v60, v[62:63], off
	v_lshl_add_u64 v[62:63], v[62:63], 0, s[100:101]
	global_load_dword v60, v[62:63], off
	v_add_f32_e32 v30, v30, v47
	v_max_f32_e32 v47, v50, v50
	v_max_f32_e32 v47, v30, v47
	v_sub_f32_e32 v50, v50, v47
	v_sub_f32_e32 v30, v30, v47
	v_mul_f32_e32 v50, 0x3fb8aa3b, v50
	v_mul_f32_e32 v30, 0x3fb8aa3b, v30
	v_exp_f32_e32 v53, v50
	v_exp_f32_e32 v52, v30
	v_add_co_u32_e32 v50, vcc, 0x43608000, v20
	v_mul_f32_e32 v30, v19, v53
	v_pk_fma_f32 v[18:19], v[18:19], v[52:53], v[30:31] op_sel_hi:[1,1,0]
	v_mul_f32_e32 v30, v53, v51
	v_fmac_f32_e32 v30, v14, v52
	v_bfe_u32 v14, v18, 16, 1
	v_add3_u32 v14, v18, v14, s88
	v_addc_co_u32_e32 v51, vcc, 0, v21, vcc
	flat_store_short_d16_hi v[50:51], v14
	s_and_saveexec_b64 s[4:5], s[36:37]
	s_cbranch_execz .LBB0_1449
	v_add_co_u32_e32 v50, vcc, 0x700000, v10
	s_nop 1
	v_addc_co_u32_e32 v51, vcc, 0, v11, vcc
	flat_store_dword v[50:51], v30 offset:512
